# NSA top-16 block selection: replace 64-step readlane rank loop by bitwise threshold search with ballots (same selection, ties to lower index)
# speedup vs baseline: 1.0775x; 1.0169x over previous
.LBB0_386:
	s_waitcnt lgkmcnt(0)
	s_lshr_b32 s0, s80, 6
	s_cmpk_lt_u32 s80, 0x400
	s_mov_b64 s[6:7], -1
	s_cbranch_scc1 .LBB0_394
	v_cmp_ne_u32_e32 vcc, s0, v152
	v_cmp_ne_u32_e64 s[6:7], 0, v152
	v_mov_b32_e32 v140, 0
	s_and_b64 s[10:11], vcc, s[6:7]
	v_lshlrev_b32_e32 v32, 6, v152
	v_mov_b32_e32 v141, 0
	v_cmp_ge_i32_e64 s[76:77], s80, v32
	s_mov_b64 s[26:27], exec
	v_mov_b32_e32 v33, 0x4e6e6b28
	v_mov_b32_e32 v34, 0x4e6e6b28
	v_mov_b32_e32 v35, 0x4e6e6b28
	v_mov_b32_e32 v36, 0x4e6e6b28
	v_mov_b32_e32 v37, 0x4e6e6b28
	v_mov_b32_e32 v38, 0x4e6e6b28
	v_mov_b32_e32 v39, 0x4e6e6b28
	v_mov_b32_e32 v40, 0x4e6e6b28
	s_and_b64 exec, s[26:27], s[10:11]
	ds_read_b32 v33, v131 offset:0
	ds_read_b32 v34, v131 offset:256
	ds_read_b32 v35, v131 offset:512
	ds_read_b32 v36, v131 offset:768
	ds_read_b32 v37, v131 offset:1024
	ds_read_b32 v38, v131 offset:1280
	ds_read_b32 v39, v131 offset:1536
	ds_read_b32 v40, v131 offset:1792
	s_waitcnt lgkmcnt(0)
	v_cndmask_b32_e64 v33, v165, v33, s[76:77]
	v_cndmask_b32_e64 v34, v165, v34, s[76:77]
	v_cndmask_b32_e64 v35, v165, v35, s[76:77]
	v_cndmask_b32_e64 v36, v165, v36, s[76:77]
	v_cndmask_b32_e64 v37, v165, v37, s[76:77]
	v_cndmask_b32_e64 v38, v165, v38, s[76:77]
	v_cndmask_b32_e64 v39, v165, v39, s[76:77]
	v_cndmask_b32_e64 v40, v165, v40, s[76:77]
	s_mov_b64 exec, s[26:27]
	s_mov_b32 s12, 0
	s_mov_b32 s13, 0
	s_mov_b32 s14, 0
	s_mov_b32 s15, 0
	s_mov_b32 s16, 0
	s_mov_b32 s17, 0
	s_mov_b32 s18, 0
	s_mov_b32 s19, 0
	s_mov_b32 s32, 0x40000000
.Ltk0_bit:
	s_or_b32 s48, s12, s32
	s_or_b32 s71, s13, s32
	s_or_b32 s73, s14, s32
	s_or_b32 s75, s15, s32
	v_cmp_le_i32_e64 s[6:7], s48, v33
	v_cmp_le_i32_e64 s[8:9], s71, v34
	v_cmp_le_i32_e64 s[20:21], s73, v35
	v_cmp_le_i32_e64 s[24:25], s75, v36
	s_bcnt1_i32_b64 s92, s[6:7]
	s_cmp_ge_u32 s92, 16
	s_cselect_b32 s12, s48, s12
	s_bcnt1_i32_b64 s92, s[8:9]
	s_cmp_ge_u32 s92, 16
	s_cselect_b32 s13, s71, s13
	s_bcnt1_i32_b64 s92, s[20:21]
	s_cmp_ge_u32 s92, 16
	s_cselect_b32 s14, s73, s14
	s_bcnt1_i32_b64 s92, s[24:25]
	s_cmp_ge_u32 s92, 16
	s_cselect_b32 s15, s75, s15
	s_or_b32 s48, s16, s32
	s_or_b32 s71, s17, s32
	s_or_b32 s73, s18, s32
	s_or_b32 s75, s19, s32
	v_cmp_le_i32_e64 s[6:7], s48, v37
	v_cmp_le_i32_e64 s[8:9], s71, v38
	v_cmp_le_i32_e64 s[20:21], s73, v39
	v_cmp_le_i32_e64 s[24:25], s75, v40
	s_bcnt1_i32_b64 s92, s[6:7]
	s_cmp_ge_u32 s92, 16
	s_cselect_b32 s16, s48, s16
	s_bcnt1_i32_b64 s92, s[8:9]
	s_cmp_ge_u32 s92, 16
	s_cselect_b32 s17, s71, s17
	s_bcnt1_i32_b64 s92, s[20:21]
	s_cmp_ge_u32 s92, 16
	s_cselect_b32 s18, s73, s18
	s_bcnt1_i32_b64 s92, s[24:25]
	s_cmp_ge_u32 s92, 16
	s_cselect_b32 s19, s75, s19
	s_lshr_b32 s32, s32, 1
	s_cmp_lg_u32 s32, 0
	s_cbranch_scc1 .Ltk0_bit
	v_cmp_lt_i32_e64 s[6:7], s12, v33
	v_cmp_eq_i32_e64 s[8:9], s12, v33
	v_cmp_eq_u32_e64 s[20:21], 0, v128
	s_bcnt1_i32_b64 s92, s[6:7]
	s_sub_i32 s92, 16, s92
.Ltk0_tie0:
	s_ff1_i32_b64 s48, s[8:9]
	s_bitset1_b64 s[6:7], s48
	s_bitset0_b64 s[8:9], s48
	s_sub_i32 s92, s92, 1
	s_cmp_gt_i32 s92, 0
	s_cbranch_scc1 .Ltk0_tie0
	v_mov_b32_e32 v41, s6
	v_mov_b32_e32 v42, s7
	v_cndmask_b32_e64 v140, v140, v41, s[20:21]
	v_cndmask_b32_e64 v141, v141, v42, s[20:21]
	v_cmp_lt_i32_e64 s[6:7], s13, v34
	v_cmp_eq_i32_e64 s[8:9], s13, v34
	v_cmp_eq_u32_e64 s[20:21], 1, v128
	s_bcnt1_i32_b64 s92, s[6:7]
	s_sub_i32 s92, 16, s92
.Ltk0_tie1:
	s_ff1_i32_b64 s48, s[8:9]
	s_bitset1_b64 s[6:7], s48
	s_bitset0_b64 s[8:9], s48
	s_sub_i32 s92, s92, 1
	s_cmp_gt_i32 s92, 0
	s_cbranch_scc1 .Ltk0_tie1
	v_mov_b32_e32 v41, s6
	v_mov_b32_e32 v42, s7
	v_cndmask_b32_e64 v140, v140, v41, s[20:21]
	v_cndmask_b32_e64 v141, v141, v42, s[20:21]
	v_cmp_lt_i32_e64 s[6:7], s14, v35
	v_cmp_eq_i32_e64 s[8:9], s14, v35
	v_cmp_eq_u32_e64 s[20:21], 2, v128
	s_bcnt1_i32_b64 s92, s[6:7]
	s_sub_i32 s92, 16, s92
.Ltk0_tie2:
	s_ff1_i32_b64 s48, s[8:9]
	s_bitset1_b64 s[6:7], s48
	s_bitset0_b64 s[8:9], s48
	s_sub_i32 s92, s92, 1
	s_cmp_gt_i32 s92, 0
	s_cbranch_scc1 .Ltk0_tie2
	v_mov_b32_e32 v41, s6
	v_mov_b32_e32 v42, s7
	v_cndmask_b32_e64 v140, v140, v41, s[20:21]
	v_cndmask_b32_e64 v141, v141, v42, s[20:21]
	v_cmp_lt_i32_e64 s[6:7], s15, v36
	v_cmp_eq_i32_e64 s[8:9], s15, v36
	v_cmp_eq_u32_e64 s[20:21], 3, v128
	s_bcnt1_i32_b64 s92, s[6:7]
	s_sub_i32 s92, 16, s92
.Ltk0_tie3:
	s_ff1_i32_b64 s48, s[8:9]
	s_bitset1_b64 s[6:7], s48
	s_bitset0_b64 s[8:9], s48
	s_sub_i32 s92, s92, 1
	s_cmp_gt_i32 s92, 0
	s_cbranch_scc1 .Ltk0_tie3
	v_mov_b32_e32 v41, s6
	v_mov_b32_e32 v42, s7
	v_cndmask_b32_e64 v140, v140, v41, s[20:21]
	v_cndmask_b32_e64 v141, v141, v42, s[20:21]
	v_cmp_lt_i32_e64 s[6:7], s16, v37
	v_cmp_eq_i32_e64 s[8:9], s16, v37
	v_cmp_eq_u32_e64 s[20:21], 4, v128
	s_bcnt1_i32_b64 s92, s[6:7]
	s_sub_i32 s92, 16, s92
.Ltk0_tie4:
	s_ff1_i32_b64 s48, s[8:9]
	s_bitset1_b64 s[6:7], s48
	s_bitset0_b64 s[8:9], s48
	s_sub_i32 s92, s92, 1
	s_cmp_gt_i32 s92, 0
	s_cbranch_scc1 .Ltk0_tie4
	v_mov_b32_e32 v41, s6
	v_mov_b32_e32 v42, s7
	v_cndmask_b32_e64 v140, v140, v41, s[20:21]
	v_cndmask_b32_e64 v141, v141, v42, s[20:21]
	v_cmp_lt_i32_e64 s[6:7], s17, v38
	v_cmp_eq_i32_e64 s[8:9], s17, v38
	v_cmp_eq_u32_e64 s[20:21], 5, v128
	s_bcnt1_i32_b64 s92, s[6:7]
	s_sub_i32 s92, 16, s92
.Ltk0_tie5:
	s_ff1_i32_b64 s48, s[8:9]
	s_bitset1_b64 s[6:7], s48
	s_bitset0_b64 s[8:9], s48
	s_sub_i32 s92, s92, 1
	s_cmp_gt_i32 s92, 0
	s_cbranch_scc1 .Ltk0_tie5
	v_mov_b32_e32 v41, s6
	v_mov_b32_e32 v42, s7
	v_cndmask_b32_e64 v140, v140, v41, s[20:21]
	v_cndmask_b32_e64 v141, v141, v42, s[20:21]
	v_cmp_lt_i32_e64 s[6:7], s18, v39
	v_cmp_eq_i32_e64 s[8:9], s18, v39
	v_cmp_eq_u32_e64 s[20:21], 6, v128
	s_bcnt1_i32_b64 s92, s[6:7]
	s_sub_i32 s92, 16, s92
.Ltk0_tie6:
	s_ff1_i32_b64 s48, s[8:9]
	s_bitset1_b64 s[6:7], s48
	s_bitset0_b64 s[8:9], s48
	s_sub_i32 s92, s92, 1
	s_cmp_gt_i32 s92, 0
	s_cbranch_scc1 .Ltk0_tie6
	v_mov_b32_e32 v41, s6
	v_mov_b32_e32 v42, s7
	v_cndmask_b32_e64 v140, v140, v41, s[20:21]
	v_cndmask_b32_e64 v141, v141, v42, s[20:21]
	v_cmp_lt_i32_e64 s[6:7], s19, v40
	v_cmp_eq_i32_e64 s[8:9], s19, v40
	v_cmp_eq_u32_e64 s[20:21], 7, v128
	s_bcnt1_i32_b64 s92, s[6:7]
	s_sub_i32 s92, 16, s92
.Ltk0_tie7:
	s_ff1_i32_b64 s48, s[8:9]
	s_bitset1_b64 s[6:7], s48
	s_bitset0_b64 s[8:9], s48
	s_sub_i32 s92, s92, 1
	s_cmp_gt_i32 s92, 0
	s_cbranch_scc1 .Ltk0_tie7
	v_mov_b32_e32 v41, s6
	v_mov_b32_e32 v42, s7
	v_cndmask_b32_e64 v140, v140, v41, s[20:21]
	v_cndmask_b32_e64 v141, v141, v42, s[20:21]
	v_mov_b32_e32 v33, 0x4e6e6b28
	v_mov_b32_e32 v34, 0x4e6e6b28
	v_mov_b32_e32 v35, 0x4e6e6b28
	v_mov_b32_e32 v36, 0x4e6e6b28
	v_mov_b32_e32 v37, 0x4e6e6b28
	v_mov_b32_e32 v38, 0x4e6e6b28
	v_mov_b32_e32 v39, 0x4e6e6b28
	v_mov_b32_e32 v40, 0x4e6e6b28
	s_and_b64 exec, s[26:27], s[10:11]
	ds_read_b32 v33, v131 offset:2048
	ds_read_b32 v34, v131 offset:2304
	ds_read_b32 v35, v131 offset:2560
	ds_read_b32 v36, v131 offset:2816
	ds_read_b32 v37, v131 offset:3072
	ds_read_b32 v38, v131 offset:3328
	ds_read_b32 v39, v131 offset:3584
	ds_read_b32 v40, v131 offset:3840
	s_waitcnt lgkmcnt(0)
	v_cndmask_b32_e64 v33, v165, v33, s[76:77]
	v_cndmask_b32_e64 v34, v165, v34, s[76:77]
	v_cndmask_b32_e64 v35, v165, v35, s[76:77]
	v_cndmask_b32_e64 v36, v165, v36, s[76:77]
	v_cndmask_b32_e64 v37, v165, v37, s[76:77]
	v_cndmask_b32_e64 v38, v165, v38, s[76:77]
	v_cndmask_b32_e64 v39, v165, v39, s[76:77]
	v_cndmask_b32_e64 v40, v165, v40, s[76:77]
	s_mov_b64 exec, s[26:27]
	s_mov_b32 s12, 0
	s_mov_b32 s13, 0
	s_mov_b32 s14, 0
	s_mov_b32 s15, 0
	s_mov_b32 s16, 0
	s_mov_b32 s17, 0
	s_mov_b32 s18, 0
	s_mov_b32 s19, 0
	s_mov_b32 s32, 0x40000000
.Ltk8_bit:
	s_or_b32 s48, s12, s32
	s_or_b32 s71, s13, s32
	s_or_b32 s73, s14, s32
	s_or_b32 s75, s15, s32
	v_cmp_le_i32_e64 s[6:7], s48, v33
	v_cmp_le_i32_e64 s[8:9], s71, v34
	v_cmp_le_i32_e64 s[20:21], s73, v35
	v_cmp_le_i32_e64 s[24:25], s75, v36
	s_bcnt1_i32_b64 s92, s[6:7]
	s_cmp_ge_u32 s92, 16
	s_cselect_b32 s12, s48, s12
	s_bcnt1_i32_b64 s92, s[8:9]
	s_cmp_ge_u32 s92, 16
	s_cselect_b32 s13, s71, s13
	s_bcnt1_i32_b64 s92, s[20:21]
	s_cmp_ge_u32 s92, 16
	s_cselect_b32 s14, s73, s14
	s_bcnt1_i32_b64 s92, s[24:25]
	s_cmp_ge_u32 s92, 16
	s_cselect_b32 s15, s75, s15
	s_or_b32 s48, s16, s32
	s_or_b32 s71, s17, s32
	s_or_b32 s73, s18, s32
	s_or_b32 s75, s19, s32
	v_cmp_le_i32_e64 s[6:7], s48, v37
	v_cmp_le_i32_e64 s[8:9], s71, v38
	v_cmp_le_i32_e64 s[20:21], s73, v39
	v_cmp_le_i32_e64 s[24:25], s75, v40
	s_bcnt1_i32_b64 s92, s[6:7]
	s_cmp_ge_u32 s92, 16
	s_cselect_b32 s16, s48, s16
	s_bcnt1_i32_b64 s92, s[8:9]
	s_cmp_ge_u32 s92, 16
	s_cselect_b32 s17, s71, s17
	s_bcnt1_i32_b64 s92, s[20:21]
	s_cmp_ge_u32 s92, 16
	s_cselect_b32 s18, s73, s18
	s_bcnt1_i32_b64 s92, s[24:25]
	s_cmp_ge_u32 s92, 16
	s_cselect_b32 s19, s75, s19
	s_lshr_b32 s32, s32, 1
	s_cmp_lg_u32 s32, 0
	s_cbranch_scc1 .Ltk8_bit
	v_cmp_lt_i32_e64 s[6:7], s12, v33
	v_cmp_eq_i32_e64 s[8:9], s12, v33
	v_cmp_eq_u32_e64 s[20:21], 8, v128
	s_bcnt1_i32_b64 s92, s[6:7]
	s_sub_i32 s92, 16, s92
.Ltk8_tie0:
	s_ff1_i32_b64 s48, s[8:9]
	s_bitset1_b64 s[6:7], s48
	s_bitset0_b64 s[8:9], s48
	s_sub_i32 s92, s92, 1
	s_cmp_gt_i32 s92, 0
	s_cbranch_scc1 .Ltk8_tie0
	v_mov_b32_e32 v41, s6
	v_mov_b32_e32 v42, s7
	v_cndmask_b32_e64 v140, v140, v41, s[20:21]
	v_cndmask_b32_e64 v141, v141, v42, s[20:21]
	v_cmp_lt_i32_e64 s[6:7], s13, v34
	v_cmp_eq_i32_e64 s[8:9], s13, v34
	v_cmp_eq_u32_e64 s[20:21], 9, v128
	s_bcnt1_i32_b64 s92, s[6:7]
	s_sub_i32 s92, 16, s92
.Ltk8_tie1:
	s_ff1_i32_b64 s48, s[8:9]
	s_bitset1_b64 s[6:7], s48
	s_bitset0_b64 s[8:9], s48
	s_sub_i32 s92, s92, 1
	s_cmp_gt_i32 s92, 0
	s_cbranch_scc1 .Ltk8_tie1
	v_mov_b32_e32 v41, s6
	v_mov_b32_e32 v42, s7
	v_cndmask_b32_e64 v140, v140, v41, s[20:21]
	v_cndmask_b32_e64 v141, v141, v42, s[20:21]
	v_cmp_lt_i32_e64 s[6:7], s14, v35
	v_cmp_eq_i32_e64 s[8:9], s14, v35
	v_cmp_eq_u32_e64 s[20:21], 10, v128
	s_bcnt1_i32_b64 s92, s[6:7]
	s_sub_i32 s92, 16, s92
.Ltk8_tie2:
	s_ff1_i32_b64 s48, s[8:9]
	s_bitset1_b64 s[6:7], s48
	s_bitset0_b64 s[8:9], s48
	s_sub_i32 s92, s92, 1
	s_cmp_gt_i32 s92, 0
	s_cbranch_scc1 .Ltk8_tie2
	v_mov_b32_e32 v41, s6
	v_mov_b32_e32 v42, s7
	v_cndmask_b32_e64 v140, v140, v41, s[20:21]
	v_cndmask_b32_e64 v141, v141, v42, s[20:21]
	v_cmp_lt_i32_e64 s[6:7], s15, v36
	v_cmp_eq_i32_e64 s[8:9], s15, v36
	v_cmp_eq_u32_e64 s[20:21], 11, v128
	s_bcnt1_i32_b64 s92, s[6:7]
	s_sub_i32 s92, 16, s92
.Ltk8_tie3:
	s_ff1_i32_b64 s48, s[8:9]
	s_bitset1_b64 s[6:7], s48
	s_bitset0_b64 s[8:9], s48
	s_sub_i32 s92, s92, 1
	s_cmp_gt_i32 s92, 0
	s_cbranch_scc1 .Ltk8_tie3
	v_mov_b32_e32 v41, s6
	v_mov_b32_e32 v42, s7
	v_cndmask_b32_e64 v140, v140, v41, s[20:21]
	v_cndmask_b32_e64 v141, v141, v42, s[20:21]
	v_cmp_lt_i32_e64 s[6:7], s16, v37
	v_cmp_eq_i32_e64 s[8:9], s16, v37
	v_cmp_eq_u32_e64 s[20:21], 12, v128
	s_bcnt1_i32_b64 s92, s[6:7]
	s_sub_i32 s92, 16, s92
.Ltk8_tie4:
	s_ff1_i32_b64 s48, s[8:9]
	s_bitset1_b64 s[6:7], s48
	s_bitset0_b64 s[8:9], s48
	s_sub_i32 s92, s92, 1
	s_cmp_gt_i32 s92, 0
	s_cbranch_scc1 .Ltk8_tie4
	v_mov_b32_e32 v41, s6
	v_mov_b32_e32 v42, s7
	v_cndmask_b32_e64 v140, v140, v41, s[20:21]
	v_cndmask_b32_e64 v141, v141, v42, s[20:21]
	v_cmp_lt_i32_e64 s[6:7], s17, v38
	v_cmp_eq_i32_e64 s[8:9], s17, v38
	v_cmp_eq_u32_e64 s[20:21], 13, v128
	s_bcnt1_i32_b64 s92, s[6:7]
	s_sub_i32 s92, 16, s92
.Ltk8_tie5:
	s_ff1_i32_b64 s48, s[8:9]
	s_bitset1_b64 s[6:7], s48
	s_bitset0_b64 s[8:9], s48
	s_sub_i32 s92, s92, 1
	s_cmp_gt_i32 s92, 0
	s_cbranch_scc1 .Ltk8_tie5
	v_mov_b32_e32 v41, s6
	v_mov_b32_e32 v42, s7
	v_cndmask_b32_e64 v140, v140, v41, s[20:21]
	v_cndmask_b32_e64 v141, v141, v42, s[20:21]
	v_cmp_lt_i32_e64 s[6:7], s18, v39
	v_cmp_eq_i32_e64 s[8:9], s18, v39
	v_cmp_eq_u32_e64 s[20:21], 14, v128
	s_bcnt1_i32_b64 s92, s[6:7]
	s_sub_i32 s92, 16, s92
.Ltk8_tie6:
	s_ff1_i32_b64 s48, s[8:9]
	s_bitset1_b64 s[6:7], s48
	s_bitset0_b64 s[8:9], s48
	s_sub_i32 s92, s92, 1
	s_cmp_gt_i32 s92, 0
	s_cbranch_scc1 .Ltk8_tie6
	v_mov_b32_e32 v41, s6
	v_mov_b32_e32 v42, s7
	v_cndmask_b32_e64 v140, v140, v41, s[20:21]
	v_cndmask_b32_e64 v141, v141, v42, s[20:21]
	v_cmp_lt_i32_e64 s[6:7], s19, v40
	v_cmp_eq_i32_e64 s[8:9], s19, v40
	v_cmp_eq_u32_e64 s[20:21], 15, v128
	s_bcnt1_i32_b64 s92, s[6:7]
	s_sub_i32 s92, 16, s92
.Ltk8_tie7:
	s_ff1_i32_b64 s48, s[8:9]
	s_bitset1_b64 s[6:7], s48
	s_bitset0_b64 s[8:9], s48
	s_sub_i32 s92, s92, 1
	s_cmp_gt_i32 s92, 0
	s_cbranch_scc1 .Ltk8_tie7
	v_mov_b32_e32 v41, s6
	v_mov_b32_e32 v42, s7
	v_cndmask_b32_e64 v140, v140, v41, s[20:21]
	v_cndmask_b32_e64 v141, v141, v42, s[20:21]
	s_mov_b64 s[6:7], 0
